# the final-norm grid barrier skips the L2 write-back (only atomics were issued since the previous barrier)
# speedup vs baseline: 1.0004x; 1.0004x over previous
.Lmybar:
	v_readlane_b32 s100, v240, 35
	v_readlane_b32 s101, v240, 36
	v_mov_b32_e32 v247, 0x23fc0
	ds_read2_b32 v[248:249], v247 offset1:1
	v_mov_b32_e32 v250, s56
	v_lshlrev_b32_e32 v250, 8, v250
	v_add_u32_e32 v250, 0x1400, v250
	v_mov_b32_e32 v251, 1
	s_add_u32 s98, s98, 1
	s_waitcnt vmcnt(0)
	s_nop 1
	global_atomic_add v252, v250, v251, s[100:101] sc0
	s_waitcnt vmcnt(0) lgkmcnt(0)
	v_mul_lo_u32 v253, v248, s98
	v_add_u32_e32 v252, 1, v252
	v_add_u32_e32 v254, 0x1000, v250
	v_cmp_eq_u32_e32 vcc, v252, v253
	s_cbranch_vccz .Lmb_local
	s_cmp_eq_u32 s99, 12
	s_cbranch_scc1 .Lmb_nowb
	buffer_wbl2 sc1
	s_waitcnt vmcnt(0)
.Lmb_nowb:
	v_mov_b32_e32 v250, 0x3400
	global_atomic_add v250, v251, s[100:101]
	buffer_inv sc1
	v_mul_lo_u32 v253, v249, s98
	v_mov_b32_e32 v255, 0
